# r11 + gdn_prep S2: in[23][h] table load issued with the first batch of loads (one serial L2 round trip less per item)
# baseline (speedup 1.0000x reference)
.LBB0_575:
	s_ashr_i32 s3, s2, 31
	s_barrier
	s_and_saveexec_b64 s[0:1], s[6:7]
	s_cbranch_execz .LBB0_582
	v_cmp_gt_i32_e32 vcc, s22, v146
	v_mov_b32_e32 v1, 0
	v_mov_b32_e32 v0, 0
	s_and_saveexec_b64 s[22:23], vcc
	s_cbranch_execz .LBB0_580
	v_add_u32_e32 v0, s25, v146
	v_ashrrev_i32_e32 v1, 31, v0
	v_readlane_b32 s26, v253, 42
	s_and_b32 s24, s24, 3
	v_lshlrev_b64 v[0:1], 5, v[0:1]
	v_readlane_b32 s27, v253, 43
	s_lshl_b32 s62, s24, 2
	v_readlane_b32 s24, v253, 38
	v_lshl_add_u64 v[0:1], s[26:27], 0, v[0:1]
	v_lshl_add_u64 v[0:1], v[0:1], 0, s[62:63]
	v_readlane_b32 s25, v253, 39
	global_load_dword v2, v[0:1], off offset:16
	s_nop 0
	global_load_dword v0, v[0:1], off
	s_load_dwordx2 s[24:25], s[24:25], 0xc0
	v_mov_b32_e32 v1, s62
	v_readlane_b32 s100, v253, 46
	v_readlane_b32 s101, v253, 47
	v_mov_b32_e32 v255, s62
	s_nop 4
	global_load_dword v255, v255, s[100:101]
	s_waitcnt lgkmcnt(0)
	global_load_dword v1, v1, s[24:25]
	s_mov_b32 s24, 0x41a00000
	s_waitcnt vmcnt(0)
	v_add_f32_e32 v1, v2, v1
	v_cmp_nlt_f32_e32 vcc, s24, v1
	s_and_saveexec_b64 s[24:25], vcc
	s_cbranch_execz .LBB0_579
	v_mul_f32_e32 v2, 0x3fb8aa3b, v1
	v_rndne_f32_e32 v3, v2
	s_mov_b32 s26, 0x3fb8aa3b
	v_sub_f32_e32 v4, v2, v3
	v_fma_f32 v2, v1, s26, -v2
	v_fmac_f32_e32 v2, 0x32a5705f, v1
	v_add_f32_e32 v2, v4, v2
	v_cvt_i32_f32_e32 v3, v3
	v_exp_f32_e32 v2, v2
	s_mov_b32 s26, 0xc2ce8ed0
	v_cmp_ngt_f32_e32 vcc, s26, v1
	s_mov_b32 s26, 0x42b17218
	v_ldexp_f32 v2, v2, v3
	v_cndmask_b32_e32 v2, 0, v2, vcc
	v_cmp_nlt_f32_e32 vcc, s26, v1
	s_mov_b32 s26, 0x3f2aaaab
	s_nop 0
	v_cndmask_b32_e32 v1, v221, v2, vcc
	v_add_f32_e32 v4, 1.0, v1
	v_add_f32_e32 v2, -1.0, v4
	v_sub_f32_e32 v3, v2, v4
	v_add_f32_e32 v3, 1.0, v3
	v_sub_f32_e32 v2, v1, v2
	v_add_f32_e32 v5, v2, v3
	v_frexp_mant_f32_e32 v6, v4
	v_cvt_f64_f32_e32 v[2:3], v4
	v_frexp_exp_i32_f64_e32 v2, v[2:3]
	v_cmp_gt_f32_e32 vcc, s26, v6
	s_mov_b32 s26, 0x3f317218
	s_nop 0
	v_subbrev_co_u32_e32 v10, vcc, 0, v2, vcc
	v_sub_u32_e32 v2, 0, v10
	v_ldexp_f32 v3, v4, v2
	v_add_f32_e32 v4, -1.0, v3
	v_add_f32_e32 v6, 1.0, v3
	v_ldexp_f32 v2, v5, v2
	v_add_f32_e32 v5, 1.0, v4
	v_add_f32_e32 v7, -1.0, v6
	v_sub_f32_e32 v5, v3, v5
	v_sub_f32_e32 v3, v3, v7
	v_add_f32_e32 v5, v2, v5
	v_add_f32_e32 v2, v2, v3
	v_add_f32_e32 v11, v6, v2
	v_rcp_f32_e32 v13, v11
	v_sub_f32_e32 v3, v6, v11
	v_add_f32_e32 v12, v2, v3
	v_add_f32_e32 v3, v4, v5
	v_mul_f32_e32 v15, v3, v13
	v_sub_f32_e32 v2, v4, v3
	v_mul_f32_e32 v4, v11, v15
	v_fma_f32 v6, v15, v11, -v4
	v_fmac_f32_e32 v6, v15, v12
	v_add_f32_e32 v14, v5, v2
	v_add_f32_e32 v2, v4, v6
	v_sub_f32_e32 v5, v3, v2
	v_pk_add_f32 v[8:9], v[2:3], v[4:5] neg_lo:[0,1] neg_hi:[0,1]
	v_mov_b32_e32 v7, v2
	v_pk_add_f32 v[2:3], v[8:9], v[6:7] neg_lo:[0,1] neg_hi:[0,1]
	s_nop 0
	v_add_f32_e32 v3, v14, v3
	v_add_f32_e32 v2, v2, v3
	v_add_f32_e32 v3, v5, v2
	v_mul_f32_e32 v14, v13, v3
	v_mul_f32_e32 v4, v11, v14
	v_fma_f32 v6, v14, v11, -v4
	v_fmac_f32_e32 v6, v14, v12
	v_sub_f32_e32 v5, v5, v3
	v_add_f32_e32 v11, v2, v5
	v_add_f32_e32 v2, v4, v6
	v_sub_f32_e32 v5, v3, v2
	v_pk_add_f32 v[8:9], v[2:3], v[4:5] neg_lo:[0,1] neg_hi:[0,1]
	v_mov_b32_e32 v7, v2
	v_pk_add_f32 v[2:3], v[8:9], v[6:7] neg_lo:[0,1] neg_hi:[0,1]
	s_nop 0
	v_add_f32_e32 v3, v11, v3
	v_add_f32_e32 v2, v2, v3
	v_add_f32_e32 v3, v15, v14
	v_add_f32_e32 v2, v5, v2
	v_sub_f32_e32 v4, v3, v15
	v_mul_f32_e32 v2, v13, v2
	v_sub_f32_e32 v4, v14, v4
	v_add_f32_e32 v4, v4, v2
	v_add_f32_e32 v6, v3, v4
	v_mul_f32_e32 v7, v6, v6
	v_fmamk_f32 v2, v7, 0x3e9b6dac, v204
	v_fmaak_f32 v35, v7, v2, 0x3f2aaada
	v_cvt_f32_i32_e32 v2, v10
	v_sub_f32_e32 v3, v6, v3
	v_sub_f32_e32 v3, v4, v3
	v_ldexp_f32 v8, v3, 1
	v_mul_f32_e32 v3, v6, v7
	v_ldexp_f32 v5, v6, 1
	v_pk_mul_f32 v[6:7], v[2:3], v[34:35]
	s_nop 0
	v_fma_f32 v4, v2, s26, -v6
	v_fmac_f32_e32 v4, 0xb102e308, v2
	v_pk_add_f32 v[2:3], v[6:7], v[4:5]
	s_mov_b32 s26, 0x7f800000
	v_sub_f32_e32 v5, v3, v5
	v_sub_f32_e32 v5, v7, v5
	v_add_f32_e32 v9, v8, v5
	v_mov_b32_e32 v8, v6
	v_pk_add_f32 v[6:7], v[2:3], v[6:7] neg_lo:[0,1] neg_hi:[0,1]
	v_pk_add_f32 v[10:11], v[2:3], v[8:9]
	v_mov_b32_e32 v5, v2
	v_mov_b32_e32 v7, v11
	v_pk_add_f32 v[12:13], v[4:5], v[6:7] neg_lo:[0,1] neg_hi:[0,1]
	v_pk_add_f32 v[4:5], v[4:5], v[6:7]
	v_mov_b32_e32 v8, v9
	v_pk_add_f32 v[6:7], v[4:5], v[2:3] op_sel:[1,0] op_sel_hi:[0,1] neg_lo:[0,1] neg_hi:[0,1]
	v_pk_add_f32 v[14:15], v[10:11], v[6:7] op_sel_hi:[1,0] neg_lo:[0,1] neg_hi:[0,1]
	v_mov_b32_e32 v10, v11
	v_mov_b32_e32 v11, v5
	v_pk_mov_b32 v[6:7], v[2:3], v[6:7] op_sel:[1,0]
	v_mov_b32_e32 v9, v2
	v_pk_add_f32 v[6:7], v[10:11], v[6:7] neg_lo:[0,1] neg_hi:[0,1]
	v_mov_b32_e32 v14, v12
	v_pk_add_f32 v[2:3], v[8:9], v[6:7] neg_lo:[0,1] neg_hi:[0,1]
	v_mov_b32_e32 v13, v5
	v_pk_add_f32 v[6:7], v[14:15], v[2:3]
	v_cmp_neq_f32_e32 vcc, s26, v1
	v_pk_add_f32 v[8:9], v[6:7], v[6:7] op_sel:[0,1] op_sel_hi:[1,0]
	s_mov_b32 s26, 0x33800000
	v_pk_add_f32 v[4:5], v[4:5], v[8:9] op_sel:[1,0] op_sel_hi:[0,1]
	v_mov_b32_e32 v7, v4
	v_pk_add_f32 v[10:11], v[6:7], v[12:13] neg_lo:[0,1] neg_hi:[0,1]
	v_mov_b32_e32 v3, v8
	v_sub_f32_e32 v5, v6, v10
	v_pk_add_f32 v[2:3], v[2:3], v[10:11] neg_lo:[0,1] neg_hi:[0,1]
	v_sub_f32_e32 v5, v12, v5
	v_add_f32_e32 v2, v2, v5
	v_add_f32_e32 v2, v2, v3
	v_add_f32_e32 v2, v4, v2
	v_cndmask_b32_e32 v2, v221, v2, vcc
	v_cmp_lt_f32_e64 vcc, |v1|, s26
	s_nop 1
	v_cndmask_b32_e32 v1, v2, v1, vcc
.LBB0_579:
	s_or_b64 exec, exec, s[24:25]
	v_readlane_b32 s24, v253, 44
	v_mov_b32_e32 v2, s62
	v_readlane_b32 s26, v253, 46
	v_readlane_b32 s27, v253, 47
	s_mov_b32 s24, 0x3fb8aa3b
	v_readlane_b32 s25, v253, 45
	s_nop 2
	v_mov_b32_e32 v2, v255
	s_waitcnt vmcnt(0)
	v_mul_f32_e32 v3, 0x3fb8aa3b, v2
	v_fma_f32 v4, v2, s24, -v3
	v_rndne_f32_e32 v5, v3
	v_fmac_f32_e32 v4, 0x32a5705f, v2
	v_sub_f32_e32 v3, v3, v5
	v_add_f32_e32 v3, v3, v4
	v_exp_f32_e32 v3, v3
	v_cvt_i32_f32_e32 v4, v5
	s_mov_b32 s24, 0xc2ce8ed0
	v_cmp_ngt_f32_e32 vcc, s24, v2
	s_mov_b32 s24, 0x42b17218
	v_ldexp_f32 v3, v3, v4
	v_cndmask_b32_e32 v3, 0, v3, vcc
	v_cmp_nlt_f32_e32 vcc, s24, v2
	s_mov_b32 s24, 0xbfb8aa3b
	s_nop 0
	v_cndmask_b32_e32 v2, v221, v3, vcc
	v_mul_f32_e64 v1, v1, -v2
	v_mul_f32_e32 v2, 0xbfb8aa3b, v0
	v_rndne_f32_e32 v3, v2
	v_sub_f32_e32 v4, v2, v3
	v_fma_f32 v2, v0, s24, -v2
	v_fmac_f32_e32 v2, 0xb2a5705f, v0
	v_add_f32_e32 v2, v4, v2
	v_exp_f32_e32 v2, v2
	v_cvt_i32_f32_e32 v3, v3
	s_mov_b32 s24, 0x42ce8ed0
	v_cmp_nlt_f32_e32 vcc, s24, v0
	s_mov_b32 s24, 0xc2b17218
	v_ldexp_f32 v2, v2, v3
	v_cndmask_b32_e32 v2, 0, v2, vcc
	v_cmp_ngt_f32_e32 vcc, s24, v0
	s_nop 1
	v_cndmask_b32_e32 v0, v221, v2, vcc
	v_add_f32_e32 v0, 1.0, v0
	v_div_scale_f32 v2, s[24:25], v0, v0, 1.0
	v_rcp_f32_e32 v3, v2
	s_nop 0
	v_fma_f32 v4, -v2, v3, 1.0
	v_fmac_f32_e32 v3, v4, v3
	v_div_scale_f32 v4, vcc, 1.0, v0, 1.0
	v_mul_f32_e32 v5, v4, v3
	v_fma_f32 v6, -v2, v5, v4
	v_fmac_f32_e32 v5, v6, v3
	v_fma_f32 v2, -v2, v5, v4
	v_div_fmas_f32 v2, v2, v3, v5
	v_div_fixup_f32 v0, v2, v0, 1.0
